# attention loop instruction selection: removed no-op canonicalising v_max(x,x), add-zero row-sum seeds and the +0 LDS address copy (7 VALU per half-step), on top of QK burst + wave 0-3 priority
# speedup vs baseline: 1.0094x; 1.0094x over previous
; #define LAS __attribute__((address_space(3)))
; __device__ __forceinline__ void unit(const Ctx& C, int xq, int idx, LAS unsigned char* lds) {
;     ...
;         f32x16 S0, S1;
; #pragma unroll
;         for (int r = 0; r < 16; ++r) { S0[r] = 0.f; S1[r] = 0.f; }
; #pragma unroll
;         for (int d0 = 0; d0 < 4; ++d0) {
;             const bf16x8 a0 = *(const LAS bf16x8*)(sb + koff + d0 * 32), a1 = *(const LAS bf16x8*)(sb + koff + 32 * 144 + d0 * 32);
;             S0 = __builtin_amdgcn_mfma_f32_32x32x16_bf16(a0, qf[d0], S0, 0, 0, 0);
;             S1 = __builtin_amdgcn_mfma_f32_32x32x16_bf16(a1, qf[d0], S1, 0, 0, 0);
;         }
;         if (j + 3 <= cw) {
; #pragma unroll
;             for (int r = 0; r < 16; ++r) { float a_ = __builtin_fmaf(S0[r], C2, b15), b_ = __builtin_fmaf(S1[r], C2, b15); asm("" : "+v"(a_)); asm("" : "+v"(b_)); S0[r] = a_; S1[r] = b_; }
.LBB0_515:
	s_add_i32 s93, s92, -4
	s_cmp_le_u32 s93, s86
	s_cselect_b64 s[34:35], -1, 0
	s_and_b64 s[34:35], s[42:43], s[34:35]
	s_andn2_b64 vcc, exec, s[34:35]
	s_cbranch_vccnz .LBB0_523
	ds_read_b128 v[64:67], v193
	ds_read_b128 v[80:83], v193 offset:4608
	ds_read_b128 v[68:71], v193 offset:32
	ds_read_b128 v[72:75], v193 offset:4640
	ds_read_b128 v[84:87], v193 offset:64
	ds_read_b128 v[88:91], v193 offset:4672
	ds_read_b128 v[92:95], v193 offset:96
	ds_read_b128 v[222:225], v193 offset:4704
	s_add_i32 s4, s92, -1
	s_mov_b64 s[56:57], -1
	s_cmp_gt_u32 s4, s86
	s_waitcnt lgkmcnt(7)
	v_mfma_f32_32x32x16_bf16 v[112:127], v[64:67], v[128:131], 0
	s_waitcnt lgkmcnt(6)
	v_mfma_f32_32x32x16_bf16 v[96:111], v[80:83], v[128:131], 0
	s_waitcnt lgkmcnt(5)
	v_mfma_f32_32x32x16_bf16 v[112:127], v[68:71], v[132:135], v[112:127]
	s_waitcnt lgkmcnt(4)
	v_mfma_f32_32x32x16_bf16 v[96:111], v[72:75], v[132:135], v[96:111]
	s_waitcnt lgkmcnt(3)
	v_mfma_f32_32x32x16_bf16 v[112:127], v[84:87], v[136:139], v[112:127]
	s_waitcnt lgkmcnt(2)
	v_mfma_f32_32x32x16_bf16 v[96:111], v[88:91], v[136:139], v[96:111]
	s_waitcnt lgkmcnt(1)
	v_mfma_f32_32x32x16_bf16 v[112:127], v[92:95], v[140:143], v[112:127]
	s_waitcnt lgkmcnt(0)
	v_mfma_f32_32x32x16_bf16 v[96:111], v[222:225], v[140:143], v[96:111]
	s_cbranch_scc1 .LBB0_518
	s_nop 8
	v_fmamk_f32 v80, v112, 0x3e38aa3b, v191
	s_nop 0
	v_fmamk_f32 v64, v96, 0x3e38aa3b, v191
	v_fmamk_f32 v81, v113, 0x3e38aa3b, v191
	v_fmamk_f32 v65, v97, 0x3e38aa3b, v191
	v_fmamk_f32 v82, v114, 0x3e38aa3b, v191
	v_fmamk_f32 v66, v98, 0x3e38aa3b, v191
	v_fmamk_f32 v83, v115, 0x3e38aa3b, v191
	v_fmamk_f32 v67, v99, 0x3e38aa3b, v191
	v_fmamk_f32 v84, v116, 0x3e38aa3b, v191
	v_fmamk_f32 v68, v100, 0x3e38aa3b, v191
	v_fmamk_f32 v85, v117, 0x3e38aa3b, v191
	v_fmamk_f32 v69, v101, 0x3e38aa3b, v191
	v_fmamk_f32 v86, v118, 0x3e38aa3b, v191
	v_fmamk_f32 v70, v102, 0x3e38aa3b, v191
	v_fmamk_f32 v87, v119, 0x3e38aa3b, v191
	v_fmamk_f32 v71, v103, 0x3e38aa3b, v191
	v_fmamk_f32 v88, v120, 0x3e38aa3b, v191
	v_fmamk_f32 v72, v104, 0x3e38aa3b, v191
	v_fmamk_f32 v89, v121, 0x3e38aa3b, v191
	v_fmamk_f32 v73, v105, 0x3e38aa3b, v191
	v_fmamk_f32 v90, v122, 0x3e38aa3b, v191
	v_fmamk_f32 v74, v106, 0x3e38aa3b, v191
	v_fmamk_f32 v91, v123, 0x3e38aa3b, v191
	v_fmamk_f32 v75, v107, 0x3e38aa3b, v191
	v_fmamk_f32 v92, v124, 0x3e38aa3b, v191
	v_fmamk_f32 v76, v108, 0x3e38aa3b, v191
	v_fmamk_f32 v93, v125, 0x3e38aa3b, v191
	v_fmamk_f32 v77, v109, 0x3e38aa3b, v191
	v_fmamk_f32 v94, v126, 0x3e38aa3b, v191
	v_fmamk_f32 v78, v110, 0x3e38aa3b, v191
	v_fmamk_f32 v95, v127, 0x3e38aa3b, v191
	v_fmamk_f32 v79, v111, 0x3e38aa3b, v191
	s_mov_b64 s[56:57], 0

; __device__ __forceinline__ void swap32(float& a, float& b) { asm volatile("s_nop 1\n\tv_permlane32_swap_b32 %0, %1\n\ts_nop 1" : "+v"(a), "+v"(b)); }
; __device__ __forceinline__ void unit(const Ctx& C, int xq, int idx, LAS unsigned char* lds) {
;     ...
;         float rm = __builtin_fmaxf(__builtin_fmaxf(S0[0], S1[0]), S0[1]);
;         rm = __builtin_fmaxf(__builtin_fmaxf(rm, S1[1]), S0[2]); rm = __builtin_fmaxf(__builtin_fmaxf(rm, S1[2]), S0[3]);
; #pragma unroll
;         for (int r = 3; r < 15; r += 2) { rm = __builtin_fmaxf(__builtin_fmaxf(rm, S1[r]), S0[r + 1]); rm = __builtin_fmaxf(__builtin_fmaxf(rm, S1[r + 1]), S0[r + 2]); }
;         rm = __builtin_fmaxf(rm, S1[15]);
;         { float ra = rm, rbv = rm; swap32(ra, rbv); rm = __builtin_fmaxf(ra, rbv); }
;         if (__any(rm > mrun + 8.f)) {
;             const float mn = __builtin_fmaxf(mrun, rm), al = __builtin_amdgcn_exp2f(mrun - mn);
;             mrun = mn; lrun *= al;
; #pragma unroll
;             for (int i = 0; i < 4; ++i)
; #pragma unroll
;                 for (int r = 0; r < 16; ++r) O[i][r] *= al;
;         }
.LBB0_520:
	s_nop 8
	v_max_f32_e32 v96, v80, v64
	v_max3_f32 v96, v96, v81, v65
	v_max3_f32 v96, v96, v82, v66
	v_max3_f32 v96, v96, v83, v67
	v_max3_f32 v96, v96, v84, v68
	v_max3_f32 v96, v96, v85, v69
	v_max3_f32 v96, v96, v86, v70
	v_max3_f32 v96, v96, v87, v71
	v_max3_f32 v96, v96, v88, v72
	v_max3_f32 v96, v96, v89, v73
	v_max3_f32 v96, v96, v90, v74
	v_max3_f32 v96, v96, v91, v75
	v_max3_f32 v96, v96, v92, v76
	v_max3_f32 v96, v96, v93, v77
	v_max3_f32 v96, v96, v94, v78
	v_max3_f32 v96, v96, v95, v79
	v_mov_b32_e32 v97, v96
	s_nop 1
	v_permlane32_swap_b32 v96, v97
	s_nop 1
	s_nop 0
	v_max_f32_e32 v96, v96, v97
	v_add_f32_e32 v97, 0x41000000, v218
	v_cmp_gt_f32_e32 vcc, v96, v97
	s_cbranch_vccz .LBB0_522
	v_max_f32_e32 v97, v218, v96
	v_sub_f32_e32 v96, v218, v97
	v_exp_f32_e32 v96, v96
	v_mov_b32_e32 v218, v97
	v_mul_f32_e32 v217, v217, v96
	v_pk_mul_f32 v[62:63], v[62:63], v[96:97] op_sel_hi:[1,0]
	v_pk_mul_f32 v[60:61], v[60:61], v[96:97] op_sel_hi:[1,0]
	v_pk_mul_f32 v[58:59], v[58:59], v[96:97] op_sel_hi:[1,0]
	v_pk_mul_f32 v[56:57], v[56:57], v[96:97] op_sel_hi:[1,0]
	v_pk_mul_f32 v[54:55], v[54:55], v[96:97] op_sel_hi:[1,0]
	v_pk_mul_f32 v[52:53], v[52:53], v[96:97] op_sel_hi:[1,0]
	v_pk_mul_f32 v[50:51], v[50:51], v[96:97] op_sel_hi:[1,0]
	v_pk_mul_f32 v[48:49], v[48:49], v[96:97] op_sel_hi:[1,0]
	v_pk_mul_f32 v[46:47], v[46:47], v[96:97] op_sel_hi:[1,0]
	v_pk_mul_f32 v[44:45], v[44:45], v[96:97] op_sel_hi:[1,0]
	v_pk_mul_f32 v[42:43], v[42:43], v[96:97] op_sel_hi:[1,0]
	v_pk_mul_f32 v[40:41], v[40:41], v[96:97] op_sel_hi:[1,0]
	v_pk_mul_f32 v[38:39], v[38:39], v[96:97] op_sel_hi:[1,0]
	v_pk_mul_f32 v[36:37], v[36:37], v[96:97] op_sel_hi:[1,0]
	v_pk_mul_f32 v[34:35], v[34:35], v[96:97] op_sel_hi:[1,0]
	v_pk_mul_f32 v[32:33], v[32:33], v[96:97] op_sel_hi:[1,0]
	v_pk_mul_f32 v[30:31], v[30:31], v[96:97] op_sel_hi:[1,0]
	v_pk_mul_f32 v[28:29], v[28:29], v[96:97] op_sel_hi:[1,0]
	v_pk_mul_f32 v[26:27], v[26:27], v[96:97] op_sel_hi:[1,0]
	v_pk_mul_f32 v[24:25], v[24:25], v[96:97] op_sel_hi:[1,0]
	v_pk_mul_f32 v[22:23], v[22:23], v[96:97] op_sel_hi:[1,0]
	v_pk_mul_f32 v[20:21], v[20:21], v[96:97] op_sel_hi:[1,0]
	v_pk_mul_f32 v[18:19], v[18:19], v[96:97] op_sel_hi:[1,0]
	v_pk_mul_f32 v[16:17], v[16:17], v[96:97] op_sel_hi:[1,0]
	v_pk_mul_f32 v[14:15], v[14:15], v[96:97] op_sel_hi:[1,0]
	v_pk_mul_f32 v[12:13], v[12:13], v[96:97] op_sel_hi:[1,0]
	v_pk_mul_f32 v[10:11], v[10:11], v[96:97] op_sel_hi:[1,0]
	v_pk_mul_f32 v[8:9], v[8:9], v[96:97] op_sel_hi:[1,0]
	v_pk_mul_f32 v[6:7], v[6:7], v[96:97] op_sel_hi:[1,0]
	v_pk_mul_f32 v[4:5], v[4:5], v[96:97] op_sel_hi:[1,0]
	v_pk_mul_f32 v[2:3], v[2:3], v[96:97] op_sel_hi:[1,0]
	v_pk_mul_f32 v[0:1], v[0:1], v[96:97] op_sel_hi:[1,0]
; #define LAS __attribute__((address_space(3)))
; __device__ __forceinline__ unsigned cvtpk(float lo, float hi) { f32x2_t v = {lo, hi}; bf16x2_t b = __builtin_convertvector(v, bf16x2_t); return __builtin_bit_cast(unsigned, b); }
; __device__ __forceinline__ void unit(const Ctx& C, int xq, int idx, LAS unsigned char* lds) {
;     ...
;         float ls0 = 0.f, ls1 = 0.f;
; #pragma unroll
;         for (int r = 0; r < 16; ++r) {
;             float a_ = __builtin_amdgcn_exp2f(S0[r] - mrun), b_ = __builtin_amdgcn_exp2f(S1[r] - mrun);
;             S0[r] = a_; S1[r] = b_; ls0 += a_; asm("" : "+v"(ls0)); ls1 += b_; asm("" : "+v"(ls1));
;         }
;         lrun += ls0 + ls1;
;         bf16x8 pb[4];
; #pragma unroll
;         for (int mm = 0; mm < 2; ++mm) {
;             u32x4 w0, w1;
;             w0.x = cvtpk(S0[8 * mm + 0], S0[8 * mm + 1]); w0.y = cvtpk(S0[8 * mm + 2], S0[8 * mm + 3]); w0.z = cvtpk(S0[8 * mm + 4], S0[8 * mm + 5]); w0.w = cvtpk(S0[8 * mm + 6], S0[8 * mm + 7]);
;             w1.x = cvtpk(S1[8 * mm + 0], S1[8 * mm + 1]); w1.y = cvtpk(S1[8 * mm + 2], S1[8 * mm + 3]); w1.z = cvtpk(S1[8 * mm + 4], S1[8 * mm + 5]); w1.w = cvtpk(S1[8 * mm + 6], S1[8 * mm + 7]);
;             pb[mm] = __builtin_bit_cast(bf16x8, w0); pb[2 + mm] = __builtin_bit_cast(bf16x8, w1);
;         }
; #pragma unroll
;         for (int kk = 0; kk < 4; ++kk)
; #pragma unroll
;             for (int i = 0; i < 4; ++i) {
;                 const bf16x8 av = *(const LAS bf16x8*)(sb + voff + i * 32 * 144 + kk * 32);
;                 O[i] = __builtin_amdgcn_mfma_f32_32x32x16_bf16(av, pb[kk], O[i], 0, 0, 0);
;             }
.LBB0_522:
	v_sub_f32_e32 v64, v64, v218
	v_exp_f32_e32 v104, v64
	v_sub_f32_e32 v65, v65, v218
	v_sub_f32_e32 v80, v80, v218
	v_exp_f32_e32 v105, v65
	v_exp_f32_e32 v80, v80
	v_sub_f32_e32 v66, v66, v218
	v_sub_f32_e32 v81, v81, v218
	v_exp_f32_e32 v106, v66
	v_sub_f32_e32 v66, v83, v218
	v_exp_f32_e32 v81, v81
	v_exp_f32_e32 v83, v66
	v_sub_f32_e32 v66, v67, v218
	v_sub_f32_e32 v82, v82, v218
	v_add_f32_e32 v65, v104, v105
	v_exp_f32_e32 v107, v66
	v_sub_f32_e32 v66, v84, v218
	v_exp_f32_e32 v82, v82
	v_exp_f32_e32 v84, v66
	v_sub_f32_e32 v66, v68, v218
	v_add_f32_e32 v65, v106, v65
	v_exp_f32_e32 v108, v66
	v_add_f32_e32 v64, v80, v81
	v_cvt_pk_bf16_f32 v80, v80, v81
	v_add_f32_e32 v65, v107, v65
	v_add_f32_e32 v64, v82, v64
	v_cvt_pk_bf16_f32 v81, v82, v83
	v_add_f32_e32 v68, v108, v65
	v_sub_f32_e32 v65, v85, v218
	v_add_f32_e32 v64, v83, v64
	v_exp_f32_e32 v85, v65
	v_sub_f32_e32 v65, v69, v218
	v_add_f32_e32 v64, v84, v64
	v_exp_f32_e32 v109, v65
	v_add_f32_e32 v69, v85, v64
	v_sub_f32_e32 v64, v86, v218
	v_exp_f32_e32 v110, v64
	ds_read_b128 v[64:67], v207 offset:18432
	v_sub_f32_e32 v86, v87, v218
	v_exp_f32_e32 v111, v86
	v_cvt_pk_bf16_f32 v82, v84, v85
	ds_read_b128 v[84:87], v207 offset:18464
	ds_read_b128 v[96:99], v207 offset:23040
	v_sub_f32_e32 v115, v91, v218
	v_cvt_pk_bf16_f32 v83, v110, v111
	v_sub_f32_e32 v94, v94, v218
	v_exp_f32_e32 v115, v115
	s_waitcnt lgkmcnt(2)
	v_mfma_f32_32x32x16_bf16 v[48:63], v[64:67], v[80:83], v[48:63]
	v_sub_f32_e32 v64, v70, v218
	v_exp_f32_e32 v112, v64
	v_sub_f32_e32 v64, v88, v218
	v_sub_f32_e32 v88, v89, v218
	v_exp_f32_e32 v70, v64
	ds_read_b128 v[64:67], v207 offset:27648
	ds_read_b128 v[100:103], v207 offset:23072
	v_exp_f32_e32 v113, v88
	v_sub_f32_e32 v88, v90, v218
	s_waitcnt lgkmcnt(2)
	v_mfma_f32_32x32x16_bf16 v[32:47], v[96:99], v[80:83], v[32:47]
	v_exp_f32_e32 v114, v88
	ds_read_b128 v[88:91], v207 offset:32256
	ds_read_b128 v[96:99], v207 offset:27680
	v_exp_f32_e32 v94, v94
	v_sub_f32_e32 v71, v71, v218
	v_add_f32_e32 v68, v109, v68
	s_waitcnt lgkmcnt(3)
	v_mfma_f32_32x32x16_bf16 v[16:31], v[64:67], v[80:83], v[16:31]
	v_sub_f32_e32 v64, v92, v218
	v_exp_f32_e32 v92, v64
	v_sub_f32_e32 v64, v93, v218
	v_exp_f32_e32 v93, v64
	v_add_f32_e32 v69, v110, v69
	s_waitcnt lgkmcnt(1)
	v_mfma_f32_32x32x16_bf16 v[0:15], v[88:91], v[80:83], v[0:15]
	v_sub_f32_e32 v80, v95, v218
	v_exp_f32_e32 v95, v80
	v_cvt_pk_bf16_f32 v80, v70, v113
	v_cvt_pk_bf16_f32 v81, v114, v115
	v_cvt_pk_bf16_f32 v82, v92, v93
	v_cvt_pk_bf16_f32 v83, v94, v95
	v_add_f32_e32 v68, v112, v68
	v_add_f32_e32 v69, v111, v69
	v_mfma_f32_32x32x16_bf16 v[48:63], v[84:87], v[80:83], v[48:63]
	v_exp_f32_e32 v84, v71
	v_sub_f32_e32 v71, v72, v218
	ds_read_b128 v[64:67], v207 offset:32288
	v_add_f32_e32 v68, v84, v68
	v_add_f32_e32 v69, v70, v69
	v_mfma_f32_32x32x16_bf16 v[32:47], v[100:103], v[80:83], v[32:47]
	v_exp_f32_e32 v100, v71
	v_sub_f32_e32 v78, v78, v218
	v_add_f32_e32 v72, v100, v68
	v_sub_f32_e32 v68, v73, v218
	v_add_f32_e32 v73, v113, v69
	s_waitcnt lgkmcnt(1)
	v_mfma_f32_32x32x16_bf16 v[16:31], v[96:99], v[80:83], v[16:31]
	v_exp_f32_e32 v96, v68
	ds_read_b128 v[68:71], v207 offset:18496
	s_nop 0
	v_add_f32_e32 v72, v96, v72
	s_waitcnt lgkmcnt(1)
	v_mfma_f32_32x32x16_bf16 v[0:15], v[64:67], v[80:83], v[0:15]
	v_cvt_pk_bf16_f32 v64, v104, v105
	v_cvt_pk_bf16_f32 v65, v106, v107
	v_cvt_pk_bf16_f32 v66, v108, v109
	v_cvt_pk_bf16_f32 v67, v112, v84
	ds_read_b128 v[80:83], v207 offset:23104
	ds_read_b128 v[84:87], v207 offset:18528
	v_add_f32_e32 v98, v114, v73
	s_waitcnt lgkmcnt(2)
	v_mfma_f32_32x32x16_bf16 v[48:63], v[68:71], v[64:67], v[48:63]
	v_sub_f32_e32 v68, v74, v218
	v_exp_f32_e32 v97, v68
	ds_read_b128 v[68:71], v207 offset:27712
	ds_read_b128 v[88:91], v207 offset:23136
	v_add_f32_e32 v98, v115, v98
	v_add_f32_e32 v99, v97, v72
	v_sub_f32_e32 v72, v75, v218
	s_waitcnt lgkmcnt(3)
	v_mfma_f32_32x32x16_bf16 v[32:47], v[80:83], v[64:67], v[32:47]
	v_exp_f32_e32 v101, v72
	ds_read_b128 v[72:75], v207 offset:32320
	ds_read_b128 v[80:83], v207 offset:27744
	s_waitcnt lgkmcnt(3)
	v_mfma_f32_32x32x16_bf16 v[16:31], v[68:71], v[64:67], v[16:31]
	v_sub_f32_e32 v68, v76, v218
	v_exp_f32_e32 v76, v68
	v_sub_f32_e32 v68, v77, v218
	v_exp_f32_e32 v77, v68
	ds_read_b128 v[68:71], v207 offset:32352
	s_waitcnt lgkmcnt(2)
	v_mfma_f32_32x32x16_bf16 v[0:15], v[72:75], v[64:67], v[0:15]
	v_sub_f32_e32 v64, v79, v218
	v_exp_f32_e32 v72, v78
	v_exp_f32_e32 v73, v64
	v_add_f32_e32 v74, v101, v99
	v_cvt_pk_bf16_f32 v64, v100, v96
	v_cvt_pk_bf16_f32 v65, v97, v101
	v_cvt_pk_bf16_f32 v66, v76, v77
	v_cvt_pk_bf16_f32 v67, v72, v73
	v_add_f32_e32 v74, v76, v74
	v_add_f32_e32 v75, v92, v98
	v_mfma_f32_32x32x16_bf16 v[48:63], v[84:87], v[64:67], v[48:63]
	s_nop 0
	v_add_f32_e32 v74, v77, v74
	v_add_f32_e32 v75, v93, v75
	v_mfma_f32_32x32x16_bf16 v[32:47], v[88:91], v[64:67], v[32:47]
	v_add_f32_e32 v72, v72, v74
	v_add_f32_e32 v75, v94, v75
	v_add_f32_e32 v72, v73, v72
	s_waitcnt lgkmcnt(1)
	v_mfma_f32_32x32x16_bf16 v[16:31], v[80:83], v[64:67], v[16:31]
	v_add_f32_e32 v74, v95, v75
	s_nop 0
	v_add_f32_e32 v72, v74, v72
	v_add_f32_e32 v217, v217, v72
	s_waitcnt lgkmcnt(0)
	v_mfma_f32_32x32x16_bf16 v[0:15], v[68:71], v[64:67], v[0:15]

; #define LAS __attribute__((address_space(3)))
; __device__ __forceinline__ void unit(const Ctx& C, int xq, int idx, LAS unsigned char* lds) {
;     ...
;         for (int d0 = 0; d0 < 4; ++d0) {
;             const bf16x8 a0 = *(const LAS bf16x8*)(sb + koff + d0 * 32), a1 = *(const LAS bf16x8*)(sb + koff + 32 * 144 + d0 * 32);
;             S0 = __builtin_amdgcn_mfma_f32_32x32x16_bf16(a0, qf[d0], S0, 0, 0, 0);
;             S1 = __builtin_amdgcn_mfma_f32_32x32x16_bf16(a1, qf[d0], S1, 0, 0, 0);
;         }
;         if (j + 3 <= cw) {
; #pragma unroll
;             for (int r = 0; r < 16; ++r) { float a_ = __builtin_fmaf(S0[r], C2, b15), b_ = __builtin_fmaf(S1[r], C2, b15); asm("" : "+v"(a_)); asm("" : "+v"(b_)); S0[r] = a_; S1[r] = b_; }
.LBB0_537:
	ds_read_b128 v[64:67], v193 offset:36864
	ds_read_b128 v[80:83], v193 offset:41472
	ds_read_b128 v[68:71], v193 offset:36896
	ds_read_b128 v[72:75], v193 offset:41504
	ds_read_b128 v[84:87], v193 offset:36928
	ds_read_b128 v[88:91], v193 offset:41536
	ds_read_b128 v[92:95], v193 offset:36960
	ds_read_b128 v[222:225], v193 offset:41568
	s_cmp_gt_u32 s92, s86
	s_waitcnt lgkmcnt(7)
	v_mfma_f32_32x32x16_bf16 v[112:127], v[64:67], v[128:131], 0
	s_waitcnt lgkmcnt(6)
	v_mfma_f32_32x32x16_bf16 v[96:111], v[80:83], v[128:131], 0
	s_waitcnt lgkmcnt(5)
	v_mfma_f32_32x32x16_bf16 v[112:127], v[68:71], v[132:135], v[112:127]
	s_waitcnt lgkmcnt(4)
	v_mfma_f32_32x32x16_bf16 v[96:111], v[72:75], v[132:135], v[96:111]
	s_waitcnt lgkmcnt(3)
	v_mfma_f32_32x32x16_bf16 v[112:127], v[84:87], v[136:139], v[112:127]
	s_waitcnt lgkmcnt(2)
	v_mfma_f32_32x32x16_bf16 v[96:111], v[88:91], v[136:139], v[96:111]
	s_waitcnt lgkmcnt(1)
	v_mfma_f32_32x32x16_bf16 v[112:127], v[92:95], v[140:143], v[112:127]
	s_waitcnt lgkmcnt(0)
	v_mfma_f32_32x32x16_bf16 v[96:111], v[222:225], v[140:143], v[96:111]
	s_cbranch_scc1 .LBB0_539
	s_nop 8
	v_fmamk_f32 v80, v112, 0x3e38aa3b, v191
	s_nop 0
	v_fmamk_f32 v64, v96, 0x3e38aa3b, v191
	v_fmamk_f32 v81, v113, 0x3e38aa3b, v191
	v_fmamk_f32 v65, v97, 0x3e38aa3b, v191
	v_fmamk_f32 v82, v114, 0x3e38aa3b, v191
	v_fmamk_f32 v66, v98, 0x3e38aa3b, v191
	v_fmamk_f32 v83, v115, 0x3e38aa3b, v191
	v_fmamk_f32 v67, v99, 0x3e38aa3b, v191
	v_fmamk_f32 v84, v116, 0x3e38aa3b, v191
	v_fmamk_f32 v68, v100, 0x3e38aa3b, v191
	v_fmamk_f32 v85, v117, 0x3e38aa3b, v191
	v_fmamk_f32 v69, v101, 0x3e38aa3b, v191
	v_fmamk_f32 v86, v118, 0x3e38aa3b, v191
	v_fmamk_f32 v70, v102, 0x3e38aa3b, v191
	v_fmamk_f32 v87, v119, 0x3e38aa3b, v191
	v_fmamk_f32 v71, v103, 0x3e38aa3b, v191
	v_fmamk_f32 v88, v120, 0x3e38aa3b, v191
	v_fmamk_f32 v72, v104, 0x3e38aa3b, v191
	v_fmamk_f32 v89, v121, 0x3e38aa3b, v191
	v_fmamk_f32 v73, v105, 0x3e38aa3b, v191
	v_fmamk_f32 v90, v122, 0x3e38aa3b, v191
	v_fmamk_f32 v74, v106, 0x3e38aa3b, v191
	v_fmamk_f32 v91, v123, 0x3e38aa3b, v191
	v_fmamk_f32 v75, v107, 0x3e38aa3b, v191
	v_fmamk_f32 v92, v124, 0x3e38aa3b, v191
	v_fmamk_f32 v76, v108, 0x3e38aa3b, v191
	v_fmamk_f32 v93, v125, 0x3e38aa3b, v191
	v_fmamk_f32 v77, v109, 0x3e38aa3b, v191
	v_fmamk_f32 v94, v126, 0x3e38aa3b, v191
	v_fmamk_f32 v78, v110, 0x3e38aa3b, v191
	v_fmamk_f32 v95, v127, 0x3e38aa3b, v191
	v_fmamk_f32 v79, v111, 0x3e38aa3b, v191
	s_mov_b64 s[56:57], 0

; #define LAS __attribute__((address_space(3)))
; __device__ __forceinline__ unsigned cvtpk(float lo, float hi) { f32x2_t v = {lo, hi}; bf16x2_t b = __builtin_convertvector(v, bf16x2_t); return __builtin_bit_cast(unsigned, b); }
; __device__ __forceinline__ void unit(const Ctx& C, int xq, int idx, LAS unsigned char* lds) {
;     ...
;         float ls0 = 0.f, ls1 = 0.f;
; #pragma unroll
;         for (int r = 0; r < 16; ++r) {
;             float a_ = __builtin_amdgcn_exp2f(S0[r] - mrun), b_ = __builtin_amdgcn_exp2f(S1[r] - mrun);
;             S0[r] = a_; S1[r] = b_; ls0 += a_; asm("" : "+v"(ls0)); ls1 += b_; asm("" : "+v"(ls1));
;         }
;         lrun += ls0 + ls1;
;         bf16x8 pb[4];
; #pragma unroll
;         for (int mm = 0; mm < 2; ++mm) {
;             u32x4 w0, w1;
;             w0.x = cvtpk(S0[8 * mm + 0], S0[8 * mm + 1]); w0.y = cvtpk(S0[8 * mm + 2], S0[8 * mm + 3]); w0.z = cvtpk(S0[8 * mm + 4], S0[8 * mm + 5]); w0.w = cvtpk(S0[8 * mm + 6], S0[8 * mm + 7]);
;             w1.x = cvtpk(S1[8 * mm + 0], S1[8 * mm + 1]); w1.y = cvtpk(S1[8 * mm + 2], S1[8 * mm + 3]); w1.z = cvtpk(S1[8 * mm + 4], S1[8 * mm + 5]); w1.w = cvtpk(S1[8 * mm + 6], S1[8 * mm + 7]);
;             pb[mm] = __builtin_bit_cast(bf16x8, w0); pb[2 + mm] = __builtin_bit_cast(bf16x8, w1);
;         }
; #pragma unroll
;         for (int kk = 0; kk < 4; ++kk)
; #pragma unroll
;             for (int i = 0; i < 4; ++i) {
;                 const bf16x8 av = *(const LAS bf16x8*)(sb + voff + i * 32 * 144 + kk * 32);
;                 O[i] = __builtin_amdgcn_mfma_f32_32x32x16_bf16(av, pb[kk], O[i], 0, 0, 0);
;             }
.LBB0_543:
	v_sub_f32_e32 v64, v64, v218
	v_exp_f32_e32 v104, v64
	v_sub_f32_e32 v65, v65, v218
	v_sub_f32_e32 v80, v80, v218
	v_exp_f32_e32 v105, v65
	v_exp_f32_e32 v80, v80
	v_sub_f32_e32 v66, v66, v218
	v_sub_f32_e32 v81, v81, v218
	v_exp_f32_e32 v106, v66
	v_sub_f32_e32 v66, v83, v218
	v_exp_f32_e32 v81, v81
	v_exp_f32_e32 v83, v66
	v_sub_f32_e32 v66, v67, v218
	v_sub_f32_e32 v82, v82, v218
	v_add_f32_e32 v65, v104, v105
	v_exp_f32_e32 v107, v66
	v_sub_f32_e32 v66, v84, v218
	v_exp_f32_e32 v82, v82
	v_exp_f32_e32 v84, v66
	v_sub_f32_e32 v66, v68, v218
	v_add_f32_e32 v65, v106, v65
	v_exp_f32_e32 v108, v66
	v_add_f32_e32 v64, v80, v81
	v_cvt_pk_bf16_f32 v80, v80, v81
	v_add_f32_e32 v65, v107, v65
	v_add_f32_e32 v64, v82, v64
	v_cvt_pk_bf16_f32 v81, v82, v83
	v_add_f32_e32 v68, v108, v65
	v_sub_f32_e32 v65, v85, v218
	v_add_f32_e32 v64, v83, v64
	v_exp_f32_e32 v85, v65
	v_sub_f32_e32 v65, v69, v218
	v_add_f32_e32 v64, v84, v64
	v_exp_f32_e32 v109, v65
	v_add_f32_e32 v69, v85, v64
	v_sub_f32_e32 v64, v86, v218
	v_exp_f32_e32 v110, v64
	ds_read_b128 v[64:67], v207 offset:55296
	v_sub_f32_e32 v86, v87, v218
	v_exp_f32_e32 v111, v86
	v_cvt_pk_bf16_f32 v82, v84, v85
	ds_read_b128 v[84:87], v207 offset:55328
	ds_read_b128 v[96:99], v207 offset:59904
	v_sub_f32_e32 v115, v91, v218
	v_cvt_pk_bf16_f32 v83, v110, v111
	v_sub_f32_e32 v94, v94, v218
	v_exp_f32_e32 v115, v115
	s_waitcnt lgkmcnt(2)
	v_mfma_f32_32x32x16_bf16 v[48:63], v[64:67], v[80:83], v[48:63]
	v_sub_f32_e32 v64, v70, v218
	v_exp_f32_e32 v112, v64
	v_sub_f32_e32 v64, v88, v218
	v_sub_f32_e32 v88, v89, v218
	v_exp_f32_e32 v70, v64
	ds_read_b128 v[64:67], v207 offset:64512
	ds_read_b128 v[100:103], v207 offset:59936
	v_exp_f32_e32 v113, v88
	v_sub_f32_e32 v88, v90, v218
	s_waitcnt lgkmcnt(2)
	v_mfma_f32_32x32x16_bf16 v[32:47], v[96:99], v[80:83], v[32:47]
	v_exp_f32_e32 v114, v88
	ds_read_b128 v[88:91], v208 offset:13824
	ds_read_b128 v[96:99], v207 offset:64544
	v_exp_f32_e32 v94, v94
	v_sub_f32_e32 v71, v71, v218
	v_add_f32_e32 v68, v109, v68
	s_waitcnt lgkmcnt(3)
	v_mfma_f32_32x32x16_bf16 v[16:31], v[64:67], v[80:83], v[16:31]
	v_sub_f32_e32 v64, v92, v218
	v_exp_f32_e32 v92, v64
	v_sub_f32_e32 v64, v93, v218
	v_exp_f32_e32 v93, v64
	v_add_f32_e32 v69, v110, v69
	s_waitcnt lgkmcnt(1)
	v_mfma_f32_32x32x16_bf16 v[0:15], v[88:91], v[80:83], v[0:15]
	v_sub_f32_e32 v80, v95, v218
	v_exp_f32_e32 v95, v80
	v_cvt_pk_bf16_f32 v80, v70, v113
	v_cvt_pk_bf16_f32 v81, v114, v115
	v_cvt_pk_bf16_f32 v82, v92, v93
	v_cvt_pk_bf16_f32 v83, v94, v95
	v_add_f32_e32 v68, v112, v68
	v_add_f32_e32 v69, v111, v69
	v_mfma_f32_32x32x16_bf16 v[48:63], v[84:87], v[80:83], v[48:63]
	v_exp_f32_e32 v84, v71
	v_sub_f32_e32 v71, v72, v218
	ds_read_b128 v[64:67], v208 offset:13856
	v_add_f32_e32 v68, v84, v68
	v_add_f32_e32 v69, v70, v69
	v_mfma_f32_32x32x16_bf16 v[32:47], v[100:103], v[80:83], v[32:47]
	v_exp_f32_e32 v100, v71
	v_sub_f32_e32 v78, v78, v218
	v_add_f32_e32 v72, v100, v68
	v_sub_f32_e32 v68, v73, v218
	v_add_f32_e32 v73, v113, v69
	s_waitcnt lgkmcnt(1)
	v_mfma_f32_32x32x16_bf16 v[16:31], v[96:99], v[80:83], v[16:31]
	v_exp_f32_e32 v96, v68
	ds_read_b128 v[68:71], v207 offset:55360
	s_nop 0
	v_add_f32_e32 v72, v96, v72
	s_waitcnt lgkmcnt(1)
	v_mfma_f32_32x32x16_bf16 v[0:15], v[64:67], v[80:83], v[0:15]
	v_cvt_pk_bf16_f32 v64, v104, v105
	v_cvt_pk_bf16_f32 v65, v106, v107
	v_cvt_pk_bf16_f32 v66, v108, v109
	v_cvt_pk_bf16_f32 v67, v112, v84
	ds_read_b128 v[80:83], v207 offset:59968
	ds_read_b128 v[84:87], v207 offset:55392
	v_add_f32_e32 v98, v114, v73
	s_waitcnt lgkmcnt(2)
	v_mfma_f32_32x32x16_bf16 v[48:63], v[68:71], v[64:67], v[48:63]
	v_sub_f32_e32 v68, v74, v218
	v_exp_f32_e32 v97, v68
	ds_read_b128 v[68:71], v207 offset:64576
	ds_read_b128 v[88:91], v207 offset:60000
	v_add_f32_e32 v98, v115, v98
	v_add_f32_e32 v99, v97, v72
	v_sub_f32_e32 v72, v75, v218
	s_waitcnt lgkmcnt(3)
	v_mfma_f32_32x32x16_bf16 v[32:47], v[80:83], v[64:67], v[32:47]
	v_exp_f32_e32 v101, v72
	ds_read_b128 v[72:75], v208 offset:13888
	ds_read_b128 v[80:83], v207 offset:64608
	s_waitcnt lgkmcnt(3)
	v_mfma_f32_32x32x16_bf16 v[16:31], v[68:71], v[64:67], v[16:31]
	v_sub_f32_e32 v68, v76, v218
	v_exp_f32_e32 v76, v68
	v_sub_f32_e32 v68, v77, v218
	v_exp_f32_e32 v77, v68
	ds_read_b128 v[68:71], v208 offset:13920
	s_waitcnt lgkmcnt(2)
	v_mfma_f32_32x32x16_bf16 v[0:15], v[72:75], v[64:67], v[0:15]
	v_sub_f32_e32 v64, v79, v218
	v_exp_f32_e32 v72, v78
	v_exp_f32_e32 v73, v64
	v_add_f32_e32 v74, v101, v99
	v_cvt_pk_bf16_f32 v64, v100, v96
	v_cvt_pk_bf16_f32 v65, v97, v101
	v_cvt_pk_bf16_f32 v66, v76, v77
	v_cvt_pk_bf16_f32 v67, v72, v73
	v_add_f32_e32 v74, v76, v74
	v_add_f32_e32 v75, v92, v98
	v_mfma_f32_32x32x16_bf16 v[48:63], v[84:87], v[64:67], v[48:63]
	s_nop 0
	v_add_f32_e32 v74, v77, v74
	v_add_f32_e32 v75, v93, v75
	v_mfma_f32_32x32x16_bf16 v[32:47], v[88:91], v[64:67], v[32:47]
	v_add_f32_e32 v72, v72, v74
	v_add_f32_e32 v75, v94, v75
	v_add_f32_e32 v72, v73, v72
	s_waitcnt lgkmcnt(1)
	v_mfma_f32_32x32x16_bf16 v[16:31], v[80:83], v[64:67], v[16:31]
	v_add_f32_e32 v74, v95, v75
	s_nop 0
	v_add_f32_e32 v72, v74, v72
	v_add_f32_e32 v217, v217, v72
	s_waitcnt lgkmcnt(0)
	v_mfma_f32_32x32x16_bf16 v[0:15], v[68:71], v[64:67], v[0:15]
	s_add_i32 s34, s92, -2
	s_cmp_ge_u32 s34, s37
	s_cbranch_scc1 .LBB0_535
